# attention causal band (tail loop): waves wholly below a key tile do not issue its 8 QK MFMAs; the 8 PV MFMAs of a tile whose P is exactly 0 are not issued
# baseline (speedup 1.0000x reference)
.LBB0_571:
	s_add_i32 s98, s84, s40
	s_lshl_b32 s98, s98, 1
	s_cmp_gt_i32 s98, s29
	v_add_u32_e32 v182, s30, v212
	ds_read_b64_tr_b16 v[178:179], v182 offset:24576
	ds_read_b64_tr_b16 v[180:181], v182 offset:25088
	s_waitcnt lgkmcnt(9)
	s_cbranch_scc1 .Lbq1_0
	v_mfma_f32_32x32x16_f16 v[98:113], v[174:177], v[138:141], v[34:49]
.Lbq1_0:
	v_add_f32_e32 v82, v66, v67
	v_add_f32_e32 v82, v68, v82
	v_add_f32_e32 v82, v69, v82
	v_add_f32_e32 v82, v70, v82
	v_add_f32_e32 v82, v71, v82
	v_cvt_pk_f16_f32 v142, v66, v67
	v_cvt_pk_f16_f32 v143, v68, v69
	ds_read_b64_tr_b16 v[174:175], v182 offset:28672
	ds_read_b64_tr_b16 v[176:177], v182 offset:29184
	v_add_f32_e32 v66, v72, v82
	s_waitcnt lgkmcnt(10)
	s_cbranch_scc1 .Lbq1_1
	v_mfma_f32_32x32x16_f16 v[98:113], v[166:169], v[130:133], v[98:113]
.Lbq1_1:
	v_add_f32_e32 v66, v73, v66
	v_add_f32_e32 v66, v74, v66
	v_add_f32_e32 v122, v75, v66
	v_cvt_pk_f16_f32 v144, v70, v71
	v_cvt_pk_f16_f32 v145, v72, v73
	ds_read_b64_tr_b16 v[66:67], v182 offset:25600
	ds_read_b64_tr_b16 v[68:69], v182 offset:26112
	s_waitcnt lgkmcnt(11)
	s_cbranch_scc1 .Lbq1_2
	v_mfma_f32_32x32x16_f16 v[98:113], v[158:161], v[118:121], v[98:113]
.Lbq1_2:
	v_add_f32_e32 v70, v76, v122
	v_add_f32_e32 v70, v77, v70
	v_add_f32_e32 v70, v78, v70
	v_add_f32_e32 v122, v79, v70
	v_cvt_pk_f16_f32 v134, v74, v75
	v_cvt_pk_f16_f32 v135, v76, v77
	ds_read_b64_tr_b16 v[70:71], v182 offset:29696
	ds_read_b64_tr_b16 v[72:73], v182 offset:30208
	s_waitcnt lgkmcnt(12)
	s_cbranch_scc1 .Lbq1_3
	v_mfma_f32_32x32x16_f16 v[98:113], v[150:153], v[114:117], v[98:113]
.Lbq1_3:
	v_add_f32_e32 v74, v80, v122
	v_add_f32_e32 v74, v81, v74
	v_add_f32_e32 v74, v50, v74
	v_add_f32_e32 v122, v51, v74
	v_cvt_pk_f16_f32 v136, v78, v79
	v_cvt_pk_f16_f32 v137, v80, v81
	ds_read_b64_tr_b16 v[74:75], v182 offset:26624
	ds_read_b64_tr_b16 v[76:77], v182 offset:27136
	s_waitcnt lgkmcnt(13)
	s_cbranch_scc1 .Lbq1_4
	v_mfma_f32_32x32x16_f16 v[82:97], v[170:173], v[138:141], v[34:49]
.Lbq1_4:
	v_add_f32_e32 v78, v52, v122
	v_add_f32_e32 v78, v53, v78
	v_add_f32_e32 v78, v54, v78
	v_add_f32_e32 v78, v55, v78
	v_cvt_pk_f16_f32 v126, v50, v51
	v_cvt_pk_f16_f32 v127, v52, v53
	ds_read_b64_tr_b16 v[50:51], v182 offset:30720
	ds_read_b64_tr_b16 v[52:53], v182 offset:31232
	s_waitcnt lgkmcnt(14)
	s_cbranch_scc1 .Lbq1_5
	v_mfma_f32_32x32x16_f16 v[82:97], v[162:165], v[130:133], v[82:97]
.Lbq1_5:
	v_add_f32_e32 v78, v56, v78
	v_add_f32_e32 v78, v57, v78
	v_add_f32_e32 v78, v58, v78
	v_add_f32_e32 v78, v59, v78
	v_cvt_pk_f16_f32 v128, v54, v55
	v_cvt_pk_f16_f32 v129, v56, v57
	ds_read_b64_tr_b16 v[54:55], v182 offset:27648
	ds_read_b64_tr_b16 v[56:57], v182 offset:28160
	s_waitcnt lgkmcnt(14)
	s_cbranch_scc1 .Lbq1_6
	v_mfma_f32_32x32x16_f16 v[82:97], v[154:157], v[118:121], v[82:97]
.Lbq1_6:
	v_add_f32_e32 v78, v60, v78
	v_add_f32_e32 v78, v61, v78
	v_add_f32_e32 v78, v62, v78
	v_add_f32_e32 v78, v63, v78
	v_cvt_pk_f16_f32 v122, v58, v59
	v_cvt_pk_f16_f32 v123, v60, v61
	ds_read_b64_tr_b16 v[58:59], v182 offset:31744
	ds_read_b64_tr_b16 v[60:61], v182 offset:32256
	s_cbranch_scc1 .Lbq1_7
	v_mfma_f32_32x32x16_f16 v[82:97], v[146:149], v[114:117], v[82:97]
.Lbq1_7:
	v_add_f32_e32 v78, v64, v78
	v_add_f32_e32 v78, v65, v78
	v_add_f32_e32 v78, 0, v78
	v_cvt_pk_f16_f32 v124, v62, v63
	v_cvt_pk_f16_f32 v125, v64, v65
	s_add_i32 s4, s40, 3
	s_cmp_ge_u32 s4, s35
	s_cselect_b64 s[70:71], -1, 0
	s_and_b64 vcc, exec, s[70:71]
	s_cbranch_vccnz .LBB0_573
	v_lshl_add_u64 v[62:63], v[194:195], 0, s[54:55]
	s_add_i32 s4, s11, s76
	s_mov_b32 s5, m0
	s_mov_b32 m0, s4
	s_nop 0
	global_load_lds_dwordx4 v[62:63], off
	s_mov_b32 m0, s5

.LBB0_587:
	s_add_i32 s98, s84, s40
	s_lshl_b32 s98, s98, 1
	s_add_i32 s98, s98, 2
	s_cmp_gt_i32 s98, s29
	v_add_u32_e32 v216, s11, v212
	ds_read_b64_tr_b16 v[186:187], v216 offset:24576
	ds_read_b64_tr_b16 v[188:189], v216 offset:25088
	s_waitcnt lgkmcnt(9)
	s_cbranch_scc1 .Lbq2_0
	v_mfma_f32_32x32x16_f16 v[66:81], v[174:177], v[138:141], v[34:49]
.Lbq2_0:
	v_add_f32_e32 v50, v98, v99
	v_add_f32_e32 v50, v100, v50
	v_add_f32_e32 v50, v101, v50
	v_add_f32_e32 v50, v102, v50
	v_add_f32_e32 v50, v103, v50
	v_cvt_pk_f16_f32 v142, v98, v99
	v_cvt_pk_f16_f32 v143, v100, v101
	ds_read_b64_tr_b16 v[182:183], v216 offset:28672
	ds_read_b64_tr_b16 v[184:185], v216 offset:29184
	v_add_f32_e32 v50, v104, v50
	v_add_f32_e32 v50, v105, v50
	v_add_f32_e32 v50, v106, v50
	v_add_f32_e32 v98, v107, v50
	s_waitcnt lgkmcnt(10)
	s_cbranch_scc1 .Lbq2_1
	v_mfma_f32_32x32x16_f16 v[66:81], v[166:169], v[130:133], v[66:81]
.Lbq2_1:
	v_cvt_pk_f16_f32 v144, v102, v103
	v_cvt_pk_f16_f32 v145, v104, v105
	ds_read_b64_tr_b16 v[178:179], v216 offset:25600
	ds_read_b64_tr_b16 v[180:181], v216 offset:26112
	s_waitcnt lgkmcnt(11)
	s_cbranch_scc1 .Lbq2_2
	v_mfma_f32_32x32x16_f16 v[66:81], v[158:161], v[118:121], v[66:81]
.Lbq2_2:
	v_add_f32_e32 v98, v108, v98
	v_add_f32_e32 v98, v109, v98
	v_add_f32_e32 v98, v110, v98
	v_add_f32_e32 v98, v111, v98
	v_cvt_pk_f16_f32 v134, v106, v107
	v_cvt_pk_f16_f32 v135, v108, v109
	ds_read_b64_tr_b16 v[106:107], v216 offset:29696
	ds_read_b64_tr_b16 v[108:109], v216 offset:30208
	s_waitcnt lgkmcnt(12)
	s_cbranch_scc1 .Lbq2_3
	v_mfma_f32_32x32x16_f16 v[66:81], v[150:153], v[114:117], v[66:81]
.Lbq2_3:
	v_add_f32_e32 v98, v112, v98
	v_add_f32_e32 v98, v113, v98
	v_add_f32_e32 v98, v82, v98
	v_add_f32_e32 v98, v83, v98
	v_cvt_pk_f16_f32 v136, v110, v111
	v_cvt_pk_f16_f32 v137, v112, v113
	ds_read_b64_tr_b16 v[102:103], v216 offset:26624
	ds_read_b64_tr_b16 v[104:105], v216 offset:27136
	s_waitcnt lgkmcnt(13)
	s_cbranch_scc1 .Lbq2_4
	v_mfma_f32_32x32x16_f16 v[50:65], v[170:173], v[138:141], v[34:49]
.Lbq2_4:
	v_add_f32_e32 v98, v84, v98
	v_add_f32_e32 v98, v85, v98
	v_add_f32_e32 v98, v86, v98
	v_add_f32_e32 v110, v87, v98
	v_cvt_pk_f16_f32 v126, v82, v83
	v_cvt_pk_f16_f32 v127, v84, v85
	ds_read_b64_tr_b16 v[98:99], v216 offset:30720
	ds_read_b64_tr_b16 v[100:101], v216 offset:31232
	s_waitcnt lgkmcnt(14)
	s_cbranch_scc1 .Lbq2_5
	v_mfma_f32_32x32x16_f16 v[50:65], v[162:165], v[130:133], v[50:65]
.Lbq2_5:
	v_add_f32_e32 v82, v88, v110
	v_add_f32_e32 v82, v89, v82
	v_add_f32_e32 v82, v90, v82
	v_add_f32_e32 v82, v91, v82
	v_cvt_pk_f16_f32 v128, v86, v87
	v_cvt_pk_f16_f32 v129, v88, v89
	ds_read_b64_tr_b16 v[86:87], v216 offset:27648
	ds_read_b64_tr_b16 v[88:89], v216 offset:28160
	s_waitcnt lgkmcnt(14)
	s_cbranch_scc1 .Lbq2_6
	v_mfma_f32_32x32x16_f16 v[50:65], v[154:157], v[118:121], v[50:65]
.Lbq2_6:
	v_add_f32_e32 v82, v92, v82
	v_add_f32_e32 v82, v93, v82
	v_add_f32_e32 v82, v94, v82
	v_add_f32_e32 v110, v95, v82
	v_cvt_pk_f16_f32 v122, v90, v91
	v_cvt_pk_f16_f32 v123, v92, v93
	ds_read_b64_tr_b16 v[82:83], v216 offset:31744
	ds_read_b64_tr_b16 v[84:85], v216 offset:32256
	s_cbranch_scc1 .Lbq2_7
	v_mfma_f32_32x32x16_f16 v[50:65], v[146:149], v[114:117], v[50:65]
.Lbq2_7:
	v_add_f32_e32 v90, v96, v110
	v_add_f32_e32 v90, v97, v90
	v_add_f32_e32 v90, 0, v90
	v_cvt_pk_f16_f32 v124, v94, v95
	v_cvt_pk_f16_f32 v125, v96, v97
	s_add_i32 s5, s40, 4
	s_cmp_ge_u32 s5, s35
	s_cselect_b64 s[30:31], -1, 0
	s_and_b64 vcc, exec, s[30:31]
	s_cbranch_vccnz .LBB0_589
	s_add_i32 s5, s68, s76
	s_mov_b32 s8, m0
	s_mov_b32 m0, s5
	s_nop 0
	global_load_lds_dwordx4 v[194:195], off
	s_mov_b32 m0, s8

.LBB0_595:
	s_lshl_b32 s99, s85, 1
	s_add_i32 s99, s99, -2
	s_waitcnt lgkmcnt(14)
	s_cmp_gt_i32 s99, s29
	s_cbranch_scc1 .Lbp2_0
	v_mfma_f32_32x32x16_f16 v[18:33], v[142:145], v[186:189], v[18:33]
.Lbp2_0:
	v_exp_f32_e32 v66, v66
	v_exp_f32_e32 v67, v67
	v_exp_f32_e32 v68, v68
	v_exp_f32_e32 v69, v69
	s_waitcnt lgkmcnt(12)
	s_cmp_gt_i32 s99, s29
	s_cbranch_scc1 .Lbp2_1
	v_mfma_f32_32x32x16_f16 v[2:17], v[142:145], v[182:185], v[2:17]
.Lbp2_1:
	v_exp_f32_e32 v70, v70
	v_exp_f32_e32 v71, v71
	v_exp_f32_e32 v72, v72
	v_exp_f32_e32 v73, v73
	v_cndmask_b32_e64 v90, 0, 1, s[24:25]
	v_cmp_ne_u32_e64 s[4:5], 1, v90
	s_andn2_b64 vcc, exec, s[24:25]
	v_add_u32_e32 v90, s11, v211
	s_cbranch_vccnz .LBB0_597
	ds_read_b128 v[174:177], v90
	ds_read_b128 v[170:173], v90 offset:512
.LBB0_597:
	s_waitcnt lgkmcnt(10)
	s_cmp_gt_i32 s99, s29
	s_cbranch_scc1 .Lbp2_2
	v_mfma_f32_32x32x16_f16 v[18:33], v[134:137], v[178:181], v[18:33]
.Lbp2_2:
	v_exp_f32_e32 v74, v74
	v_exp_f32_e32 v75, v75
	v_exp_f32_e32 v76, v76
	v_exp_f32_e32 v77, v77
	s_and_b64 vcc, exec, s[4:5]
	s_cbranch_vccnz .LBB0_599
	ds_read_b128 v[166:169], v90 offset:2048
	ds_read_b128 v[162:165], v90 offset:2560
.LBB0_599:
	s_waitcnt lgkmcnt(8)
	s_cmp_gt_i32 s99, s29
	s_cbranch_scc1 .Lbp2_3
	v_mfma_f32_32x32x16_f16 v[2:17], v[134:137], v[106:109], v[2:17]
.Lbp2_3:
	v_exp_f32_e32 v78, v78
	v_exp_f32_e32 v79, v79
	v_exp_f32_e32 v80, v80
	v_exp_f32_e32 v81, v81
	s_and_b64 vcc, exec, s[4:5]
	s_cbranch_vccnz .LBB0_601
	ds_read_b128 v[158:161], v90 offset:4096
	ds_read_b128 v[154:157], v90 offset:4608
.LBB0_601:
	s_waitcnt lgkmcnt(6)
	s_cmp_gt_i32 s99, s29
	s_cbranch_scc1 .Lbp2_4
	v_mfma_f32_32x32x16_f16 v[18:33], v[126:129], v[102:105], v[18:33]
.Lbp2_4:
	v_exp_f32_e32 v50, v50
	v_exp_f32_e32 v51, v51
	v_exp_f32_e32 v52, v52
	v_exp_f32_e32 v53, v53
	s_and_b64 vcc, exec, s[4:5]
	s_cbranch_vccnz .LBB0_603
	ds_read_b128 v[150:153], v90 offset:6144
	ds_read_b128 v[146:149], v90 offset:6656
.LBB0_603:
	s_waitcnt lgkmcnt(4)
	s_cmp_gt_i32 s99, s29
	s_cbranch_scc1 .Lbp2_5
	v_mfma_f32_32x32x16_f16 v[2:17], v[126:129], v[98:101], v[2:17]
.Lbp2_5:
	v_exp_f32_e32 v54, v54
	v_exp_f32_e32 v55, v55
	v_exp_f32_e32 v56, v56
	v_exp_f32_e32 v57, v57
	s_waitcnt lgkmcnt(2)
	s_cmp_gt_i32 s99, s29
	s_cbranch_scc1 .Lbp2_6
	v_mfma_f32_32x32x16_f16 v[18:33], v[122:125], v[86:89], v[18:33]
.Lbp2_6:
	v_exp_f32_e32 v58, v58
	v_exp_f32_e32 v59, v59
	v_exp_f32_e32 v60, v60
	v_exp_f32_e32 v61, v61
	s_waitcnt lgkmcnt(0)
	s_cmp_gt_i32 s99, s29
	s_cbranch_scc1 .Lbp2_7
	v_mfma_f32_32x32x16_f16 v[2:17], v[122:125], v[82:85], v[2:17]
.Lbp2_7:
	v_exp_f32_e32 v62, v62
	v_exp_f32_e32 v63, v63
	v_exp_f32_e32 v64, v64
	v_exp_f32_e32 v65, v65
	s_mov_b64 s[4:5], -1
	s_and_b64 vcc, exec, s[30:31]
	s_cbranch_vccz .LBB0_615
	s_and_b64 vcc, exec, s[70:71]
	s_cbranch_vccz .LBB0_606
	s_waitcnt vmcnt(0) lgkmcnt(0)
	s_barrier
	s_mov_b64 s[4:5], 0
